# GEMM K-loops: B-fragment ds_reads of phases 2/5/6 issued inside the previous phase's MFMA block (MFMA-LDS interleave), all three main instances
# baseline (speedup 1.0000x reference)
.LBB0_258:
	ds_read_b128 v[172:175], v0
	ds_read_b128 v[176:179], v0 offset:1024
	ds_read_b128 v[180:183], v0 offset:2048
	ds_read_b128 v[186:189], v0 offset:3072
	s_add_i32 s40, s2, 0xffffff80
	s_ashr_i32 s41, s40, 31
	s_add_i32 s38, s2, 0xffffff40
	s_lshl_b64 s[46:47], s[40:41], 1
	s_add_u32 s3, s12, s46
	s_addc_u32 s17, s13, s47
	s_ashr_i32 s39, s38, 31
	s_lshl_b64 s[38:39], s[38:39], 1
	s_add_u32 s25, s84, s38
	s_addc_u32 s38, s85, s39
	s_add_u32 s25, s25, 0xfffff880
	s_addc_u32 s38, s38, -1
	s_cmpk_lt_i32 s40, 0x400
	s_cselect_b32 s3, s3, s25
	s_cselect_b32 s17, s17, s38
	s_add_u32 s38, s3, s10
	v_add_u32_e32 v184, 0xc000, v144
	s_addc_u32 s39, s17, s11
	v_readfirstlane_b32 s3, v184
	v_add_u32_e32 v184, 0xc000, v145
	v_add_u32_e32 v171, v164, v156
	v_lshl_add_u64 v[194:195], s[38:39], 0, v[132:133]
	s_mov_b32 m0, s3
	v_readfirstlane_b32 s3, v184
	ds_read_b128 v[190:193], v171
	ds_read_b128 v[198:201], v171 offset:1024
	ds_read_b128 v[202:205], v165
	ds_read_b128 v[218:221], v165 offset:1024
	ds_read_b128 v[222:225], v166
	ds_read_b128 v[226:229], v166 offset:1024
	ds_read_b128 v[230:233], v167
	ds_read_b128 v[234:237], v167 offset:1024
	global_load_lds_dwordx4 v[194:195], off
	v_lshl_add_u64 v[194:195], s[38:39], 0, v[130:131]
	s_mov_b32 m0, s3
	s_nop 0
	global_load_lds_dwordx4 v[194:195], off
	s_waitcnt lgkmcnt(8)
	s_barrier
	s_waitcnt lgkmcnt(0)
	s_waitcnt lgkmcnt(0)
	v_mfma_f32_16x16x32_bf16 v[118:121], v[172:175], v[190:193], v[118:121]
	v_mfma_f32_16x16x32_bf16 v[126:129], v[180:183], v[190:193], v[126:129]
	ds_read_b128 v[238:241], v168
	v_mfma_f32_16x16x32_bf16 v[122:125], v[172:175], v[202:205], v[122:125]
	v_mfma_f32_16x16x32_bf16 v[114:117], v[180:183], v[202:205], v[114:117]
	v_mfma_f32_16x16x32_bf16 v[110:113], v[172:175], v[222:225], v[110:113]
	v_mfma_f32_16x16x32_bf16 v[106:109], v[180:183], v[222:225], v[106:109]
	ds_read_b128 v[242:245], v168 offset:1024
	v_mfma_f32_16x16x32_bf16 v[102:105], v[172:175], v[230:233], v[102:105]
	v_mfma_f32_16x16x32_bf16 v[98:101], v[180:183], v[230:233], v[98:101]
	v_mfma_f32_16x16x32_bf16 v[118:121], v[176:179], v[198:201], v[118:121]
	v_mfma_f32_16x16x32_bf16 v[126:129], v[186:189], v[198:201], v[126:129]
	ds_read_b128 v[246:249], v168 offset:2048
	v_mfma_f32_16x16x32_bf16 v[122:125], v[176:179], v[218:221], v[122:125]
	v_mfma_f32_16x16x32_bf16 v[114:117], v[186:189], v[218:221], v[114:117]
	v_mfma_f32_16x16x32_bf16 v[110:113], v[176:179], v[226:229], v[110:113]
	v_mfma_f32_16x16x32_bf16 v[106:109], v[186:189], v[226:229], v[106:109]
	ds_read_b128 v[194:197], v168 offset:3072
	v_mfma_f32_16x16x32_bf16 v[102:105], v[176:179], v[234:237], v[102:105]
	v_mfma_f32_16x16x32_bf16 v[98:101], v[186:189], v[234:237], v[98:101]
	s_barrier
	v_add_u32_e32 v184, s33, v154
	v_lshl_add_u64 v[206:207], s[30:31], 0, v[140:141]
	v_readfirstlane_b32 s3, v184
	v_lshl_add_u64 v[214:215], v[206:207], 0, s[20:21]
	s_mov_b32 m0, s3
	v_add_u32_e32 v184, s33, v155
	global_load_lds_dwordx4 v[214:215], off
	v_lshl_add_u64 v[214:215], s[30:31], 0, v[138:139]
	v_readfirstlane_b32 s3, v184
	v_lshl_add_u64 v[250:251], v[214:215], 0, s[20:21]
	s_mov_b32 m0, s3
	s_add_i32 s9, s9, 2
	global_load_lds_dwordx4 v[250:251], off
	s_barrier
	s_waitcnt lgkmcnt(0)
	s_waitcnt lgkmcnt(0)
	v_mfma_f32_16x16x32_bf16 v[94:97], v[238:241], v[190:193], v[94:97]
	v_mfma_f32_16x16x32_bf16 v[90:93], v[246:249], v[190:193], v[90:93]
	v_mfma_f32_16x16x32_bf16 v[86:89], v[238:241], v[202:205], v[86:89]
	v_mfma_f32_16x16x32_bf16 v[82:85], v[246:249], v[202:205], v[82:85]
	v_mfma_f32_16x16x32_bf16 v[78:81], v[238:241], v[222:225], v[78:81]
	v_mfma_f32_16x16x32_bf16 v[74:77], v[246:249], v[222:225], v[74:77]
	v_mfma_f32_16x16x32_bf16 v[70:73], v[238:241], v[230:233], v[70:73]
	v_mfma_f32_16x16x32_bf16 v[66:69], v[246:249], v[230:233], v[66:69]
	v_mfma_f32_16x16x32_bf16 v[94:97], v[242:245], v[198:201], v[94:97]
	v_mfma_f32_16x16x32_bf16 v[90:93], v[194:197], v[198:201], v[90:93]
	v_mfma_f32_16x16x32_bf16 v[86:89], v[242:245], v[218:221], v[86:89]
	v_mfma_f32_16x16x32_bf16 v[82:85], v[194:197], v[218:221], v[82:85]
	v_mfma_f32_16x16x32_bf16 v[78:81], v[242:245], v[226:229], v[78:81]
	v_mfma_f32_16x16x32_bf16 v[74:77], v[194:197], v[226:229], v[74:77]
	v_mfma_f32_16x16x32_bf16 v[70:73], v[242:245], v[234:237], v[70:73]
	v_mfma_f32_16x16x32_bf16 v[66:69], v[194:197], v[234:237], v[66:69]
	s_sub_i32 s94, s2, 64
	s_lshl_b64 s[38:39], s[94:95], 1
	s_add_u32 s3, s12, s38
	s_addc_u32 s17, s13, s39
	s_add_u32 s25, s84, s38
	s_addc_u32 s38, s85, s39
	s_add_u32 s25, s25, 0xfffff800
	s_addc_u32 s38, s38, -1
	s_cmpk_lt_u32 s94, 0x400
	s_cselect_b32 s3, s3, s25
	s_cselect_b32 s17, s17, s38
	s_add_u32 s38, s3, s28
	s_addc_u32 s39, s17, s29
	v_readfirstlane_b32 s25, v144
	v_lshl_add_u64 v[250:251], s[38:39], 0, v[132:133]
	s_mov_b32 m0, s25
	v_readfirstlane_b32 s25, v145
	s_barrier
	ds_read_b128 v[190:193], v171 offset:16384
	ds_read_b128 v[198:201], v171 offset:17408
	ds_read_b128 v[202:205], v165 offset:16384
	ds_read_b128 v[218:221], v165 offset:17408
	ds_read_b128 v[222:225], v166 offset:16384
	ds_read_b128 v[226:229], v166 offset:17408
	ds_read_b128 v[230:233], v167 offset:16384
	ds_read_b128 v[234:237], v167 offset:17408
	global_load_lds_dwordx4 v[250:251], off
	v_lshl_add_u64 v[250:251], s[38:39], 0, v[130:131]
	s_mov_b32 m0, s25
	s_nop 0
	global_load_lds_dwordx4 v[250:251], off
	s_barrier
	s_waitcnt lgkmcnt(0)
	s_waitcnt lgkmcnt(0)
	v_mfma_f32_16x16x32_bf16 v[62:65], v[172:175], v[190:193], v[62:65]
	v_mfma_f32_16x16x32_bf16 v[58:61], v[180:183], v[190:193], v[58:61]
	v_mfma_f32_16x16x32_bf16 v[54:57], v[172:175], v[202:205], v[54:57]
	v_mfma_f32_16x16x32_bf16 v[50:53], v[180:183], v[202:205], v[50:53]
	v_mfma_f32_16x16x32_bf16 v[46:49], v[172:175], v[222:225], v[46:49]
	v_mfma_f32_16x16x32_bf16 v[42:45], v[180:183], v[222:225], v[42:45]
	v_mfma_f32_16x16x32_bf16 v[38:41], v[172:175], v[230:233], v[38:41]
	v_mfma_f32_16x16x32_bf16 v[34:37], v[180:183], v[230:233], v[34:37]
	v_mfma_f32_16x16x32_bf16 v[62:65], v[176:179], v[198:201], v[62:65]
	v_mfma_f32_16x16x32_bf16 v[58:61], v[186:189], v[198:201], v[58:61]
	v_mfma_f32_16x16x32_bf16 v[54:57], v[176:179], v[218:221], v[54:57]
	v_mfma_f32_16x16x32_bf16 v[50:53], v[186:189], v[218:221], v[50:53]
	v_mfma_f32_16x16x32_bf16 v[46:49], v[176:179], v[226:229], v[46:49]
	v_mfma_f32_16x16x32_bf16 v[42:45], v[186:189], v[226:229], v[42:45]
	v_mfma_f32_16x16x32_bf16 v[38:41], v[176:179], v[234:237], v[38:41]
	v_mfma_f32_16x16x32_bf16 v[34:37], v[186:189], v[234:237], v[34:37]
	s_barrier
	v_add_u32_e32 v174, s86, v154
	v_lshl_add_u64 v[250:251], s[30:31], 0, v[136:137]
	v_readfirstlane_b32 s25, v174
	v_add_u32_e32 v174, s86, v155
	v_lshl_add_u64 v[172:173], v[250:251], 0, s[20:21]
	s_mov_b32 m0, s25
	v_lshl_add_u64 v[208:209], s[30:31], 0, v[134:135]
	v_readfirstlane_b32 s25, v174
	global_load_lds_dwordx4 v[172:173], off
	v_lshl_add_u64 v[172:173], v[208:209], 0, s[20:21]
	s_mov_b32 m0, s25
	s_nop 0
	global_load_lds_dwordx4 v[172:173], off
	s_waitcnt vmcnt(6)
	s_barrier
	v_mfma_f32_16x16x32_bf16 v[30:33], v[238:241], v[190:193], v[30:33]
	v_mfma_f32_16x16x32_bf16 v[26:29], v[246:249], v[190:193], v[26:29]
	ds_read_b128 v[172:175], v169
	v_mfma_f32_16x16x32_bf16 v[22:25], v[238:241], v[202:205], v[22:25]
	v_mfma_f32_16x16x32_bf16 v[18:21], v[246:249], v[202:205], v[18:21]
	v_mfma_f32_16x16x32_bf16 v[14:17], v[238:241], v[222:225], v[14:17]
	v_mfma_f32_16x16x32_bf16 v[10:13], v[246:249], v[222:225], v[10:13]
	ds_read_b128 v[176:179], v169 offset:1024
	v_mfma_f32_16x16x32_bf16 v[6:9], v[238:241], v[230:233], v[6:9]
	v_mfma_f32_16x16x32_bf16 v[2:5], v[246:249], v[230:233], v[2:5]
	v_mfma_f32_16x16x32_bf16 v[30:33], v[242:245], v[198:201], v[30:33]
	v_mfma_f32_16x16x32_bf16 v[26:29], v[194:197], v[198:201], v[26:29]
	ds_read_b128 v[180:183], v169 offset:2048
	v_mfma_f32_16x16x32_bf16 v[22:25], v[242:245], v[218:221], v[22:25]
	v_mfma_f32_16x16x32_bf16 v[18:21], v[194:197], v[218:221], v[18:21]
	v_mfma_f32_16x16x32_bf16 v[14:17], v[242:245], v[226:229], v[14:17]
	v_mfma_f32_16x16x32_bf16 v[10:13], v[194:197], v[226:229], v[10:13]
	ds_read_b128 v[186:189], v169 offset:3072
	v_mfma_f32_16x16x32_bf16 v[6:9], v[242:245], v[234:237], v[6:9]
	v_mfma_f32_16x16x32_bf16 v[2:5], v[194:197], v[234:237], v[2:5]
	s_barrier
	s_add_u32 s38, s3, s10
	v_add_u32_e32 v184, 0x4000, v144
	s_addc_u32 s39, s17, s11
	v_readfirstlane_b32 s3, v184
	v_add_u32_e32 v184, 0x4000, v145
	v_lshl_add_u64 v[234:235], s[38:39], 0, v[132:133]
	s_mov_b32 m0, s3
	v_readfirstlane_b32 s3, v184
	ds_read_b128 v[190:193], v171 offset:32768
	ds_read_b128 v[194:197], v171 offset:33792
	ds_read_b128 v[198:201], v165 offset:32768
	ds_read_b128 v[202:205], v165 offset:33792
	ds_read_b128 v[218:221], v166 offset:32768
	ds_read_b128 v[222:225], v166 offset:33792
	ds_read_b128 v[226:229], v167 offset:32768
	ds_read_b128 v[230:233], v167 offset:33792
	global_load_lds_dwordx4 v[234:235], off
	v_lshl_add_u64 v[234:235], s[38:39], 0, v[130:131]
	s_mov_b32 m0, s3
	s_nop 0
	global_load_lds_dwordx4 v[234:235], off
	s_waitcnt lgkmcnt(8)
	s_barrier
	s_waitcnt lgkmcnt(0)
	s_waitcnt lgkmcnt(0)
	v_mfma_f32_16x16x32_bf16 v[118:121], v[172:175], v[190:193], v[118:121]
	v_mfma_f32_16x16x32_bf16 v[126:129], v[180:183], v[190:193], v[126:129]
	ds_read_b128 v[234:237], v170
	v_mfma_f32_16x16x32_bf16 v[122:125], v[172:175], v[198:201], v[122:125]
	v_mfma_f32_16x16x32_bf16 v[114:117], v[180:183], v[198:201], v[114:117]
	v_mfma_f32_16x16x32_bf16 v[110:113], v[172:175], v[218:221], v[110:113]
	v_mfma_f32_16x16x32_bf16 v[106:109], v[180:183], v[218:221], v[106:109]
	ds_read_b128 v[238:241], v170 offset:1024
	v_mfma_f32_16x16x32_bf16 v[102:105], v[172:175], v[226:229], v[102:105]
	v_mfma_f32_16x16x32_bf16 v[98:101], v[180:183], v[226:229], v[98:101]
	v_mfma_f32_16x16x32_bf16 v[118:121], v[176:179], v[194:197], v[118:121]
	v_mfma_f32_16x16x32_bf16 v[126:129], v[186:189], v[194:197], v[126:129]
	ds_read_b128 v[242:245], v170 offset:2048
	v_mfma_f32_16x16x32_bf16 v[122:125], v[176:179], v[202:205], v[122:125]
	v_mfma_f32_16x16x32_bf16 v[114:117], v[186:189], v[202:205], v[114:117]
	v_mfma_f32_16x16x32_bf16 v[110:113], v[176:179], v[222:225], v[110:113]
	v_mfma_f32_16x16x32_bf16 v[106:109], v[186:189], v[222:225], v[106:109]
	ds_read_b128 v[246:249], v170 offset:3072
	v_mfma_f32_16x16x32_bf16 v[102:105], v[176:179], v[230:233], v[102:105]
	v_mfma_f32_16x16x32_bf16 v[98:101], v[186:189], v[230:233], v[98:101]
	s_barrier
	v_readfirstlane_b32 s3, v158
	v_lshl_add_u64 v[206:207], v[206:207], 0, s[52:53]
	s_mov_b32 m0, s3
	v_readfirstlane_b32 s3, v159
	global_load_lds_dwordx4 v[206:207], off
	v_lshl_add_u64 v[206:207], v[214:215], 0, s[52:53]
	s_mov_b32 m0, s3
	s_nop 0
	global_load_lds_dwordx4 v[206:207], off
	s_barrier
	s_waitcnt lgkmcnt(0)
	s_waitcnt lgkmcnt(0)
	v_mfma_f32_16x16x32_bf16 v[94:97], v[234:237], v[190:193], v[94:97]
	v_mfma_f32_16x16x32_bf16 v[90:93], v[242:245], v[190:193], v[90:93]
	v_mfma_f32_16x16x32_bf16 v[86:89], v[234:237], v[198:201], v[86:89]
	v_mfma_f32_16x16x32_bf16 v[82:85], v[242:245], v[198:201], v[82:85]
	v_mfma_f32_16x16x32_bf16 v[78:81], v[234:237], v[218:221], v[78:81]
	v_mfma_f32_16x16x32_bf16 v[74:77], v[242:245], v[218:221], v[74:77]
	v_mfma_f32_16x16x32_bf16 v[70:73], v[234:237], v[226:229], v[70:73]
	v_mfma_f32_16x16x32_bf16 v[66:69], v[242:245], v[226:229], v[66:69]
	v_mfma_f32_16x16x32_bf16 v[94:97], v[238:241], v[194:197], v[94:97]
	v_mfma_f32_16x16x32_bf16 v[90:93], v[246:249], v[194:197], v[90:93]
	v_mfma_f32_16x16x32_bf16 v[86:89], v[238:241], v[202:205], v[86:89]
	v_mfma_f32_16x16x32_bf16 v[82:85], v[246:249], v[202:205], v[82:85]
	v_mfma_f32_16x16x32_bf16 v[78:81], v[238:241], v[222:225], v[78:81]
	v_mfma_f32_16x16x32_bf16 v[74:77], v[246:249], v[222:225], v[74:77]
	v_mfma_f32_16x16x32_bf16 v[70:73], v[238:241], v[230:233], v[70:73]
	v_mfma_f32_16x16x32_bf16 v[66:69], v[246:249], v[230:233], v[66:69]
	s_mov_b32 s3, s95
	s_lshl_b64 s[38:39], s[2:3], 1
	s_add_u32 s3, s12, s38
	s_addc_u32 s17, s13, s39
	s_add_u32 s25, s84, s38
	s_addc_u32 s38, s85, s39
	s_add_u32 s25, s25, 0xfffff800
	s_addc_u32 s38, s38, -1
	s_cmpk_lt_u32 s2, 0x400
	s_cselect_b32 s3, s3, s25
	s_cselect_b32 s17, s17, s38
	s_add_u32 s38, s3, s28
	s_addc_u32 s39, s17, s29
	v_readfirstlane_b32 s3, v160
	v_lshl_add_u64 v[206:207], s[38:39], 0, v[132:133]
	s_mov_b32 m0, s3
	v_readfirstlane_b32 s3, v161
	s_barrier
	ds_read_b128 v[190:193], v171 offset:49152
	ds_read_b128 v[194:197], v171 offset:50176
	ds_read_b128 v[198:201], v165 offset:49152
	ds_read_b128 v[202:205], v165 offset:50176
	ds_read_b128 v[218:221], v166 offset:49152
	ds_read_b128 v[222:225], v166 offset:50176
	ds_read_b128 v[226:229], v167 offset:49152
	ds_read_b128 v[230:233], v167 offset:50176
	global_load_lds_dwordx4 v[206:207], off
	v_lshl_add_u64 v[206:207], s[38:39], 0, v[130:131]
	s_mov_b32 m0, s3
	s_nop 0
	global_load_lds_dwordx4 v[206:207], off
	s_barrier
	s_waitcnt lgkmcnt(0)
	s_waitcnt lgkmcnt(0)
	v_mfma_f32_16x16x32_bf16 v[62:65], v[172:175], v[190:193], v[62:65]
	v_mfma_f32_16x16x32_bf16 v[58:61], v[180:183], v[190:193], v[58:61]
	v_mfma_f32_16x16x32_bf16 v[54:57], v[172:175], v[198:201], v[54:57]
	v_mfma_f32_16x16x32_bf16 v[50:53], v[180:183], v[198:201], v[50:53]
	v_mfma_f32_16x16x32_bf16 v[46:49], v[172:175], v[218:221], v[46:49]
	v_mfma_f32_16x16x32_bf16 v[42:45], v[180:183], v[218:221], v[42:45]
	v_mfma_f32_16x16x32_bf16 v[38:41], v[172:175], v[226:229], v[38:41]
	v_mfma_f32_16x16x32_bf16 v[34:37], v[180:183], v[226:229], v[34:37]
	v_mfma_f32_16x16x32_bf16 v[62:65], v[176:179], v[194:197], v[62:65]
	v_mfma_f32_16x16x32_bf16 v[58:61], v[186:189], v[194:197], v[58:61]
	v_mfma_f32_16x16x32_bf16 v[54:57], v[176:179], v[202:205], v[54:57]
	v_mfma_f32_16x16x32_bf16 v[50:53], v[186:189], v[202:205], v[50:53]
	v_mfma_f32_16x16x32_bf16 v[46:49], v[176:179], v[222:225], v[46:49]
	v_mfma_f32_16x16x32_bf16 v[42:45], v[186:189], v[222:225], v[42:45]
	v_mfma_f32_16x16x32_bf16 v[38:41], v[176:179], v[230:233], v[38:41]
	v_mfma_f32_16x16x32_bf16 v[34:37], v[186:189], v[230:233], v[34:37]
	s_barrier
	v_readfirstlane_b32 s3, v162
	v_lshl_add_u64 v[172:173], v[250:251], 0, s[52:53]
	s_mov_b32 m0, s3
	v_readfirstlane_b32 s3, v163
	global_load_lds_dwordx4 v[172:173], off
	v_lshl_add_u64 v[172:173], v[208:209], 0, s[52:53]
	s_mov_b32 m0, s3
	s_nop 0
	global_load_lds_dwordx4 v[172:173], off
	s_waitcnt vmcnt(6)
	s_barrier
	v_mfma_f32_16x16x32_bf16 v[30:33], v[234:237], v[190:193], v[30:33]
	v_mfma_f32_16x16x32_bf16 v[26:29], v[242:245], v[190:193], v[26:29]
	v_mfma_f32_16x16x32_bf16 v[22:25], v[234:237], v[198:201], v[22:25]
	v_mfma_f32_16x16x32_bf16 v[18:21], v[242:245], v[198:201], v[18:21]
	v_mfma_f32_16x16x32_bf16 v[14:17], v[234:237], v[218:221], v[14:17]
	v_mfma_f32_16x16x32_bf16 v[10:13], v[242:245], v[218:221], v[10:13]
	v_mfma_f32_16x16x32_bf16 v[6:9], v[234:237], v[226:229], v[6:9]
	v_mfma_f32_16x16x32_bf16 v[2:5], v[242:245], v[226:229], v[2:5]
	v_mfma_f32_16x16x32_bf16 v[30:33], v[238:241], v[194:197], v[30:33]
	v_mfma_f32_16x16x32_bf16 v[26:29], v[246:249], v[194:197], v[26:29]
	v_mfma_f32_16x16x32_bf16 v[22:25], v[238:241], v[202:205], v[22:25]
	v_mfma_f32_16x16x32_bf16 v[18:21], v[246:249], v[202:205], v[18:21]
	v_mfma_f32_16x16x32_bf16 v[14:17], v[238:241], v[222:225], v[14:17]
	v_mfma_f32_16x16x32_bf16 v[10:13], v[246:249], v[222:225], v[10:13]
	v_mfma_f32_16x16x32_bf16 v[6:9], v[238:241], v[230:233], v[6:9]
	v_mfma_f32_16x16x32_bf16 v[2:5], v[246:249], v[230:233], v[2:5]
	s_addk_i32 s2, 0x80
	s_add_u32 s30, s30, 0x100
	s_addc_u32 s31, s31, 0
	s_cmp_ge_i32 s9, s8
	s_barrier
	s_cbranch_scc0 .LBB0_258
	v_mov_b32_e32 v134, v157
	v_or_b32_e32 v135, 0x400, v143
	v_or_b32_e32 v136, 0x800, v143
	v_or_b32_e32 v137, 0xc00, v143
	v_mov_b32_e32 v140, v156
	s_mov_b32 s84, 0x8000
	v_readlane_b32 s85, v255, 4
	v_readlane_b32 s94, v255, 5
	v_mov_b32_e32 v250, 0x3a27c5ac
	v_mov_b32_e32 v251, 0x260

.LBB0_839:
	ds_read_b128 v[170:173], v163
	ds_read_b128 v[174:177], v163 offset:1024
	ds_read_b128 v[178:181], v163 offset:2048
	ds_read_b128 v[186:189], v163 offset:3072
	s_add_i32 s39, s25, 64
	s_add_i32 s55, s52, s25
	s_ashr_i32 s56, s39, 31
	s_add_i32 s58, s55, 64
	s_cmp_lt_i32 s39, s14
	s_cselect_b32 s57, s56, 0
	s_cselect_b32 s56, s39, s58
	s_lshl_b64 s[56:57], s[56:57], 1
	s_add_u32 s56, s9, s56
	v_add_u32_e32 v206, 0xc000, v144
	s_addc_u32 s57, s17, s57
	v_readfirstlane_b32 s39, v206
	v_add_u32_e32 v206, 0xc000, v145
	v_add_u32_e32 v184, v162, v154
	v_lshl_add_u64 v[182:183], s[56:57], 0, v[0:1]
	s_mov_b32 m0, s39
	v_readfirstlane_b32 s39, v206
	ds_read_b128 v[190:193], v184
	ds_read_b128 v[194:197], v184 offset:1024
	ds_read_b128 v[198:201], v164
	ds_read_b128 v[202:205], v164 offset:1024
	ds_read_b128 v[218:221], v165
	ds_read_b128 v[222:225], v165 offset:1024
	ds_read_b128 v[226:229], v166
	ds_read_b128 v[230:233], v166 offset:1024
	global_load_lds_dwordx4 v[182:183], off
	v_lshl_add_u64 v[182:183], s[56:57], 0, v[130:131]
	s_mov_b32 m0, s39
	s_nop 0
	global_load_lds_dwordx4 v[182:183], off
	s_waitcnt lgkmcnt(8)
	s_barrier
	s_waitcnt lgkmcnt(0)
	s_waitcnt lgkmcnt(0)
	v_mfma_f32_16x16x32_bf16 v[118:121], v[170:173], v[190:193], v[118:121]
	v_mfma_f32_16x16x32_bf16 v[126:129], v[178:181], v[190:193], v[126:129]
	ds_read_b128 v[234:237], v167
	v_mfma_f32_16x16x32_bf16 v[122:125], v[170:173], v[198:201], v[122:125]
	v_mfma_f32_16x16x32_bf16 v[114:117], v[178:181], v[198:201], v[114:117]
	v_mfma_f32_16x16x32_bf16 v[110:113], v[170:173], v[218:221], v[110:113]
	v_mfma_f32_16x16x32_bf16 v[106:109], v[178:181], v[218:221], v[106:109]
	ds_read_b128 v[238:241], v167 offset:1024
	v_mfma_f32_16x16x32_bf16 v[102:105], v[170:173], v[226:229], v[102:105]
	v_mfma_f32_16x16x32_bf16 v[98:101], v[178:181], v[226:229], v[98:101]
	v_mfma_f32_16x16x32_bf16 v[118:121], v[174:177], v[194:197], v[118:121]
	v_mfma_f32_16x16x32_bf16 v[126:129], v[186:189], v[194:197], v[126:129]
	ds_read_b128 v[242:245], v167 offset:2048
	v_mfma_f32_16x16x32_bf16 v[122:125], v[174:177], v[202:205], v[122:125]
	v_mfma_f32_16x16x32_bf16 v[114:117], v[186:189], v[202:205], v[114:117]
	v_mfma_f32_16x16x32_bf16 v[110:113], v[174:177], v[222:225], v[110:113]
	v_mfma_f32_16x16x32_bf16 v[106:109], v[186:189], v[222:225], v[106:109]
	ds_read_b128 v[246:249], v167 offset:3072
	v_mfma_f32_16x16x32_bf16 v[102:105], v[174:177], v[230:233], v[102:105]
	v_mfma_f32_16x16x32_bf16 v[98:101], v[186:189], v[230:233], v[98:101]
	s_barrier
	v_add_u32_e32 v208, s33, v141
	v_lshl_add_u64 v[182:183], v[138:139], 0, s[2:3]
	v_readfirstlane_b32 s39, v208
	v_lshl_add_u64 v[206:207], v[182:183], 0, s[36:37]
	s_mov_b32 m0, s39
	v_add_u32_e32 v214, s33, v142
	global_load_lds_dwordx4 v[206:207], off
	v_lshl_add_u64 v[206:207], v[136:137], 0, s[2:3]
	v_readfirstlane_b32 s39, v214
	v_lshl_add_u64 v[208:209], v[206:207], 0, s[36:37]
	s_mov_b32 m0, s39
	s_add_i32 s24, s24, 2
	global_load_lds_dwordx4 v[208:209], off
	s_barrier
	s_waitcnt lgkmcnt(0)
	s_waitcnt lgkmcnt(0)
	v_mfma_f32_16x16x32_bf16 v[94:97], v[234:237], v[190:193], v[94:97]
	v_mfma_f32_16x16x32_bf16 v[90:93], v[242:245], v[190:193], v[90:93]
	v_mfma_f32_16x16x32_bf16 v[86:89], v[234:237], v[198:201], v[86:89]
	v_mfma_f32_16x16x32_bf16 v[82:85], v[242:245], v[198:201], v[82:85]
	v_mfma_f32_16x16x32_bf16 v[78:81], v[234:237], v[218:221], v[78:81]
	v_mfma_f32_16x16x32_bf16 v[74:77], v[242:245], v[218:221], v[74:77]
	v_mfma_f32_16x16x32_bf16 v[70:73], v[234:237], v[226:229], v[70:73]
	v_mfma_f32_16x16x32_bf16 v[66:69], v[242:245], v[226:229], v[66:69]
	v_mfma_f32_16x16x32_bf16 v[94:97], v[238:241], v[194:197], v[94:97]
	v_mfma_f32_16x16x32_bf16 v[90:93], v[246:249], v[194:197], v[90:93]
	v_mfma_f32_16x16x32_bf16 v[86:89], v[238:241], v[202:205], v[86:89]
	v_mfma_f32_16x16x32_bf16 v[82:85], v[246:249], v[202:205], v[82:85]
	v_mfma_f32_16x16x32_bf16 v[78:81], v[238:241], v[222:225], v[78:81]
	v_mfma_f32_16x16x32_bf16 v[74:77], v[246:249], v[222:225], v[74:77]
	v_mfma_f32_16x16x32_bf16 v[70:73], v[238:241], v[230:233], v[70:73]
	v_mfma_f32_16x16x32_bf16 v[66:69], v[246:249], v[230:233], v[66:69]
	s_add_i32 s39, s25, 0x80
	s_ashr_i32 s56, s39, 31
	s_add_i32 s58, s55, 0x80
	s_cmp_lt_i32 s39, s14
	s_cselect_b32 s57, s56, 0
	s_cselect_b32 s56, s39, s58
	s_lshl_b64 s[56:57], s[56:57], 1
	s_add_u32 s58, s10, s56
	s_addc_u32 s59, s11, s57
	v_readfirstlane_b32 s63, v144
	v_lshl_add_u64 v[208:209], s[58:59], 0, v[0:1]
	s_mov_b32 m0, s63
	s_barrier
	ds_read_b128 v[190:193], v184 offset:16384
	ds_read_b128 v[194:197], v184 offset:17408
	ds_read_b128 v[198:201], v164 offset:16384
	ds_read_b128 v[202:205], v164 offset:17408
	ds_read_b128 v[218:221], v165 offset:16384
	ds_read_b128 v[222:225], v165 offset:17408
	ds_read_b128 v[226:229], v166 offset:16384
	ds_read_b128 v[230:233], v166 offset:17408
	global_load_lds_dwordx4 v[208:209], off
	v_lshl_add_u64 v[208:209], s[58:59], 0, v[130:131]
	v_readfirstlane_b32 s58, v145
	s_mov_b32 m0, s58
	s_nop 0
	global_load_lds_dwordx4 v[208:209], off
	s_barrier
	s_waitcnt lgkmcnt(0)
	s_waitcnt lgkmcnt(0)
	v_mfma_f32_16x16x32_bf16 v[62:65], v[170:173], v[190:193], v[62:65]
	v_mfma_f32_16x16x32_bf16 v[58:61], v[178:181], v[190:193], v[58:61]
	v_mfma_f32_16x16x32_bf16 v[54:57], v[170:173], v[198:201], v[54:57]
	v_mfma_f32_16x16x32_bf16 v[50:53], v[178:181], v[198:201], v[50:53]
	v_mfma_f32_16x16x32_bf16 v[46:49], v[170:173], v[218:221], v[46:49]
	v_mfma_f32_16x16x32_bf16 v[42:45], v[178:181], v[218:221], v[42:45]
	v_mfma_f32_16x16x32_bf16 v[38:41], v[170:173], v[226:229], v[38:41]
	v_mfma_f32_16x16x32_bf16 v[34:37], v[178:181], v[226:229], v[34:37]
	v_mfma_f32_16x16x32_bf16 v[62:65], v[174:177], v[194:197], v[62:65]
	v_mfma_f32_16x16x32_bf16 v[58:61], v[186:189], v[194:197], v[58:61]
	v_mfma_f32_16x16x32_bf16 v[54:57], v[174:177], v[202:205], v[54:57]
	v_mfma_f32_16x16x32_bf16 v[50:53], v[186:189], v[202:205], v[50:53]
	v_mfma_f32_16x16x32_bf16 v[46:49], v[174:177], v[222:225], v[46:49]
	v_mfma_f32_16x16x32_bf16 v[42:45], v[186:189], v[222:225], v[42:45]
	v_mfma_f32_16x16x32_bf16 v[38:41], v[174:177], v[230:233], v[38:41]
	v_mfma_f32_16x16x32_bf16 v[34:37], v[186:189], v[230:233], v[34:37]
	s_barrier
	v_add_u32_e32 v172, s86, v141
	v_lshl_add_u64 v[208:209], v[134:135], 0, s[2:3]
	v_readfirstlane_b32 s58, v172
	v_add_u32_e32 v172, s86, v142
	v_lshl_add_u64 v[170:171], v[208:209], 0, s[36:37]
	s_mov_b32 m0, s58
	v_lshl_add_u64 v[214:215], v[132:133], 0, s[2:3]
	v_readfirstlane_b32 s58, v172
	global_load_lds_dwordx4 v[170:171], off
	v_lshl_add_u64 v[170:171], v[214:215], 0, s[36:37]
	s_mov_b32 m0, s58
	s_nop 0
	global_load_lds_dwordx4 v[170:171], off
	s_waitcnt vmcnt(6)
	s_barrier
	v_mfma_f32_16x16x32_bf16 v[30:33], v[234:237], v[190:193], v[30:33]
	v_mfma_f32_16x16x32_bf16 v[26:29], v[242:245], v[190:193], v[26:29]
	ds_read_b128 v[170:173], v168
	v_mfma_f32_16x16x32_bf16 v[22:25], v[234:237], v[198:201], v[22:25]
	v_mfma_f32_16x16x32_bf16 v[18:21], v[242:245], v[198:201], v[18:21]
	v_mfma_f32_16x16x32_bf16 v[14:17], v[234:237], v[218:221], v[14:17]
	v_mfma_f32_16x16x32_bf16 v[10:13], v[242:245], v[218:221], v[10:13]
	ds_read_b128 v[174:177], v168 offset:1024
	v_mfma_f32_16x16x32_bf16 v[6:9], v[234:237], v[226:229], v[6:9]
	v_mfma_f32_16x16x32_bf16 v[2:5], v[242:245], v[226:229], v[2:5]
	v_mfma_f32_16x16x32_bf16 v[30:33], v[238:241], v[194:197], v[30:33]
	v_mfma_f32_16x16x32_bf16 v[26:29], v[246:249], v[194:197], v[26:29]
	ds_read_b128 v[178:181], v168 offset:2048
	v_mfma_f32_16x16x32_bf16 v[22:25], v[238:241], v[202:205], v[22:25]
	v_mfma_f32_16x16x32_bf16 v[18:21], v[246:249], v[202:205], v[18:21]
	v_mfma_f32_16x16x32_bf16 v[14:17], v[238:241], v[222:225], v[14:17]
	v_mfma_f32_16x16x32_bf16 v[10:13], v[246:249], v[222:225], v[10:13]
	ds_read_b128 v[186:189], v168 offset:3072
	v_mfma_f32_16x16x32_bf16 v[6:9], v[238:241], v[230:233], v[6:9]
	v_mfma_f32_16x16x32_bf16 v[2:5], v[246:249], v[230:233], v[2:5]
	s_barrier
	s_add_u32 s56, s9, s56
	v_add_u32_e32 v236, 0x4000, v144
	s_addc_u32 s57, s17, s57
	v_readfirstlane_b32 s58, v236
	v_lshl_add_u64 v[234:235], s[56:57], 0, v[0:1]
	s_mov_b32 m0, s58
	v_add_u32_e32 v236, 0x4000, v145
	ds_read_b128 v[190:193], v184 offset:32768
	ds_read_b128 v[194:197], v184 offset:33792
	ds_read_b128 v[198:201], v164 offset:32768
	ds_read_b128 v[202:205], v164 offset:33792
	ds_read_b128 v[218:221], v165 offset:32768
	ds_read_b128 v[222:225], v165 offset:33792
	ds_read_b128 v[226:229], v166 offset:32768
	ds_read_b128 v[230:233], v166 offset:33792
	global_load_lds_dwordx4 v[234:235], off
	v_lshl_add_u64 v[234:235], s[56:57], 0, v[130:131]
	v_readfirstlane_b32 s56, v236
	s_mov_b32 m0, s56
	s_nop 0
	global_load_lds_dwordx4 v[234:235], off
	s_waitcnt lgkmcnt(8)
	s_barrier
	s_waitcnt lgkmcnt(0)
	s_waitcnt lgkmcnt(0)
	v_mfma_f32_16x16x32_bf16 v[118:121], v[170:173], v[190:193], v[118:121]
	v_mfma_f32_16x16x32_bf16 v[126:129], v[178:181], v[190:193], v[126:129]
	ds_read_b128 v[234:237], v169
	v_mfma_f32_16x16x32_bf16 v[122:125], v[170:173], v[198:201], v[122:125]
	v_mfma_f32_16x16x32_bf16 v[114:117], v[178:181], v[198:201], v[114:117]
	v_mfma_f32_16x16x32_bf16 v[110:113], v[170:173], v[218:221], v[110:113]
	v_mfma_f32_16x16x32_bf16 v[106:109], v[178:181], v[218:221], v[106:109]
	ds_read_b128 v[238:241], v169 offset:1024
	v_mfma_f32_16x16x32_bf16 v[102:105], v[170:173], v[226:229], v[102:105]
	v_mfma_f32_16x16x32_bf16 v[98:101], v[178:181], v[226:229], v[98:101]
	v_mfma_f32_16x16x32_bf16 v[118:121], v[174:177], v[194:197], v[118:121]
	v_mfma_f32_16x16x32_bf16 v[126:129], v[186:189], v[194:197], v[126:129]
	ds_read_b128 v[242:245], v169 offset:2048
	v_mfma_f32_16x16x32_bf16 v[122:125], v[174:177], v[202:205], v[122:125]
	v_mfma_f32_16x16x32_bf16 v[114:117], v[186:189], v[202:205], v[114:117]
	v_mfma_f32_16x16x32_bf16 v[110:113], v[174:177], v[222:225], v[110:113]
	v_mfma_f32_16x16x32_bf16 v[106:109], v[186:189], v[222:225], v[106:109]
	ds_read_b128 v[246:249], v169 offset:3072
	v_mfma_f32_16x16x32_bf16 v[102:105], v[174:177], v[230:233], v[102:105]
	v_mfma_f32_16x16x32_bf16 v[98:101], v[186:189], v[230:233], v[98:101]
	s_barrier
	v_readfirstlane_b32 s56, v156
	v_lshl_add_u64 v[182:183], v[182:183], 0, s[60:61]
	s_mov_b32 m0, s56
	v_readfirstlane_b32 s56, v157
	global_load_lds_dwordx4 v[182:183], off
	v_lshl_add_u64 v[182:183], v[206:207], 0, s[60:61]
	s_mov_b32 m0, s56
	s_nop 0
	global_load_lds_dwordx4 v[182:183], off
	s_barrier
	s_waitcnt lgkmcnt(0)
	s_waitcnt lgkmcnt(0)
	v_mfma_f32_16x16x32_bf16 v[94:97], v[234:237], v[190:193], v[94:97]
	v_mfma_f32_16x16x32_bf16 v[90:93], v[242:245], v[190:193], v[90:93]
	v_mfma_f32_16x16x32_bf16 v[86:89], v[234:237], v[198:201], v[86:89]
	v_mfma_f32_16x16x32_bf16 v[82:85], v[242:245], v[198:201], v[82:85]
	v_mfma_f32_16x16x32_bf16 v[78:81], v[234:237], v[218:221], v[78:81]
	v_mfma_f32_16x16x32_bf16 v[74:77], v[242:245], v[218:221], v[74:77]
	v_mfma_f32_16x16x32_bf16 v[70:73], v[234:237], v[226:229], v[70:73]
	v_mfma_f32_16x16x32_bf16 v[66:69], v[242:245], v[226:229], v[66:69]
	v_mfma_f32_16x16x32_bf16 v[94:97], v[238:241], v[194:197], v[94:97]
	v_mfma_f32_16x16x32_bf16 v[90:93], v[246:249], v[194:197], v[90:93]
	v_mfma_f32_16x16x32_bf16 v[86:89], v[238:241], v[202:205], v[86:89]
	v_mfma_f32_16x16x32_bf16 v[82:85], v[246:249], v[202:205], v[82:85]
	v_mfma_f32_16x16x32_bf16 v[78:81], v[238:241], v[222:225], v[78:81]
	v_mfma_f32_16x16x32_bf16 v[74:77], v[246:249], v[222:225], v[74:77]
	v_mfma_f32_16x16x32_bf16 v[70:73], v[238:241], v[230:233], v[70:73]
	v_mfma_f32_16x16x32_bf16 v[66:69], v[246:249], v[230:233], v[66:69]
	s_addk_i32 s25, 0xc0
	s_ashr_i32 s56, s25, 31
	s_addk_i32 s55, 0xc0
	s_cmp_lt_i32 s25, s14
	s_cselect_b32 s57, s56, 0
	s_cselect_b32 s56, s25, s55
	s_lshl_b64 s[56:57], s[56:57], 1
	s_add_u32 s56, s10, s56
	s_addc_u32 s57, s11, s57
	v_readfirstlane_b32 s25, v158
	v_lshl_add_u64 v[182:183], s[56:57], 0, v[0:1]
	s_mov_b32 m0, s25
	v_readfirstlane_b32 s25, v159
	s_barrier
	ds_read_b128 v[190:193], v184 offset:49152
	ds_read_b128 v[194:197], v184 offset:50176
	ds_read_b128 v[198:201], v164 offset:49152
	ds_read_b128 v[202:205], v164 offset:50176
	ds_read_b128 v[218:221], v165 offset:49152
	ds_read_b128 v[222:225], v165 offset:50176
	ds_read_b128 v[226:229], v166 offset:49152
	ds_read_b128 v[230:233], v166 offset:50176
	global_load_lds_dwordx4 v[182:183], off
	v_lshl_add_u64 v[182:183], s[56:57], 0, v[130:131]
	s_mov_b32 m0, s25
	s_nop 0
	global_load_lds_dwordx4 v[182:183], off
	s_barrier
	s_waitcnt lgkmcnt(0)
	s_waitcnt lgkmcnt(0)
	v_mfma_f32_16x16x32_bf16 v[62:65], v[170:173], v[190:193], v[62:65]
	v_mfma_f32_16x16x32_bf16 v[58:61], v[178:181], v[190:193], v[58:61]
	v_mfma_f32_16x16x32_bf16 v[54:57], v[170:173], v[198:201], v[54:57]
	v_mfma_f32_16x16x32_bf16 v[50:53], v[178:181], v[198:201], v[50:53]
	v_mfma_f32_16x16x32_bf16 v[46:49], v[170:173], v[218:221], v[46:49]
	v_mfma_f32_16x16x32_bf16 v[42:45], v[178:181], v[218:221], v[42:45]
	v_mfma_f32_16x16x32_bf16 v[38:41], v[170:173], v[226:229], v[38:41]
	v_mfma_f32_16x16x32_bf16 v[34:37], v[178:181], v[226:229], v[34:37]
	v_mfma_f32_16x16x32_bf16 v[62:65], v[174:177], v[194:197], v[62:65]
	v_mfma_f32_16x16x32_bf16 v[58:61], v[186:189], v[194:197], v[58:61]
	v_mfma_f32_16x16x32_bf16 v[54:57], v[174:177], v[202:205], v[54:57]
	v_mfma_f32_16x16x32_bf16 v[50:53], v[186:189], v[202:205], v[50:53]
	v_mfma_f32_16x16x32_bf16 v[46:49], v[174:177], v[222:225], v[46:49]
	v_mfma_f32_16x16x32_bf16 v[42:45], v[186:189], v[222:225], v[42:45]
	v_mfma_f32_16x16x32_bf16 v[38:41], v[174:177], v[230:233], v[38:41]
	v_mfma_f32_16x16x32_bf16 v[34:37], v[186:189], v[230:233], v[34:37]
	s_barrier
	v_readfirstlane_b32 s25, v160
	v_lshl_add_u64 v[170:171], v[208:209], 0, s[60:61]
	s_mov_b32 m0, s25
	v_readfirstlane_b32 s25, v161
	global_load_lds_dwordx4 v[170:171], off
	v_lshl_add_u64 v[170:171], v[214:215], 0, s[60:61]
	s_mov_b32 m0, s25
	s_nop 0
	global_load_lds_dwordx4 v[170:171], off
	s_waitcnt vmcnt(6)
	s_barrier
	v_mfma_f32_16x16x32_bf16 v[30:33], v[234:237], v[190:193], v[30:33]
	v_mfma_f32_16x16x32_bf16 v[26:29], v[242:245], v[190:193], v[26:29]
	v_mfma_f32_16x16x32_bf16 v[22:25], v[234:237], v[198:201], v[22:25]
	v_mfma_f32_16x16x32_bf16 v[18:21], v[242:245], v[198:201], v[18:21]
	v_mfma_f32_16x16x32_bf16 v[14:17], v[234:237], v[218:221], v[14:17]
	v_mfma_f32_16x16x32_bf16 v[10:13], v[242:245], v[218:221], v[10:13]
	v_mfma_f32_16x16x32_bf16 v[6:9], v[234:237], v[226:229], v[6:9]
	v_mfma_f32_16x16x32_bf16 v[2:5], v[242:245], v[226:229], v[2:5]
	v_mfma_f32_16x16x32_bf16 v[30:33], v[238:241], v[194:197], v[30:33]
	v_mfma_f32_16x16x32_bf16 v[26:29], v[246:249], v[194:197], v[26:29]
	v_mfma_f32_16x16x32_bf16 v[22:25], v[238:241], v[202:205], v[22:25]
	v_mfma_f32_16x16x32_bf16 v[18:21], v[246:249], v[202:205], v[18:21]
	v_mfma_f32_16x16x32_bf16 v[14:17], v[238:241], v[222:225], v[14:17]
	v_mfma_f32_16x16x32_bf16 v[10:13], v[246:249], v[222:225], v[10:13]
	v_mfma_f32_16x16x32_bf16 v[6:9], v[238:241], v[230:233], v[6:9]
	v_mfma_f32_16x16x32_bf16 v[2:5], v[246:249], v[230:233], v[2:5]
	v_lshl_add_u64 v[132:133], v[132:133], 0, s[36:37]
	v_lshl_add_u64 v[134:135], v[134:135], 0, s[36:37]
	v_lshl_add_u64 v[136:137], v[136:137], 0, s[36:37]
	v_lshl_add_u64 v[138:139], v[138:139], 0, s[36:37]
	s_cmp_ge_i32 s24, s8
	s_mov_b32 s25, s39
	s_barrier
	s_cbranch_scc0 .LBB0_839
	v_mov_b32_e32 v132, v155
	v_or_b32_e32 v133, 0x400, v143
	v_or_b32_e32 v134, 0x800, v143
	v_or_b32_e32 v135, 0xc00, v143
	v_mov_b32_e32 v136, v154
